# nt policy on the mixer phase's write-once OX/MIX stores only, plus the final-norm whole-line XB load
# speedup vs baseline: 1.0156x; 1.0156x over previous
; __device__ __forceinline__ unsigned cvt_pk_bf16(float lo, float hi) { unsigned r; asm volatile("v_cvt_pk_bf16_f32 %0, %1, %2" : "=v"(r) : "v"(lo), "v"(hi)); return r; }
; __device__ __forceinline__ float bflo(unsigned w) { return __uint_as_float(w << 16); }
; __device__ __forceinline__ float bfhi(unsigned w) { return __uint_as_float(w & 0xffff0000u); }
; PHASE_FN void sgu_block(const Params& p, unsigned char* lds, int l, int g, int ch0, int nch) {
;     ...
;         u32x2 uw[8];
; #pragma unroll
;         for (int pb = 0; pb < 8; ++pb) uw[pb] = *(const u32x2*)(Z + (size_t)(tok0 + 16 * pb + lr) * ZW + ZSU + ocol);
;         asm volatile("s_waitcnt lgkmcnt(0)" ::: "memory"); __builtin_amdgcn_s_barrier(); asm volatile("" ::: "memory");
;         bf16x8 af[4];
; #pragma unroll
;         for (int ks = 0; ks < 4; ++ks)
; #pragma unroll
;             for (int i = 0; i < 8; ++i) af[ks][i] = (short)vt[(32 * ks + 8 * q4 + i) * SP + 16 * wid + lr];
; #pragma unroll
;         for (int pb = 0; pb < 8; ++pb) {
;             f32x4 a = (f32x4){0.f, 0.f, 0.f, 0.f};
; #pragma unroll
;             for (int ks = 0; ks < 4; ++ks) { const bf16x8 bf = *(const bf16x8*)(wl + (16 * pb + lr) * SP + 32 * ks + 8 * q4); a = __builtin_amdgcn_mfma_f32_16x16x32_bf16(af[ks], bf, a, 0, 0, 0); }
;             const f32x2 u0 = gelu_pk((f32x2){bflo(uw[pb].x), bfhi(uw[pb].x)}), u1 = gelu_pk((f32x2){bflo(uw[pb].y), bfhi(uw[pb].y)});
;             u32x2 w; w.x = cvt_pk_bf16((a[0] + bs[pb]) * u0.x, (a[1] + bs[pb]) * u0.y); w.y = cvt_pk_bf16((a[2] + bs[pb]) * u1.x, (a[3] + bs[pb]) * u1.y);
;             *(u32x2*)(MIX + (size_t)(tok0 + 16 * pb + lr) * D + 512 + ocol) = w;
;         }
.LBB0_253:
	v_add_u32_e32 v32, s12, v91
	v_add_u32_e32 v152, 0xffff0000, v32
	v_mad_u64_u32 v[24:25], s[14:15], v152, s1, v[42:43]
	v_add_u32_e32 v72, 0xffff0010, v32
	v_add_u32_e32 v68, 0xffff0020, v32
	v_add_u32_e32 v64, 0xffff0030, v32
	v_mad_u64_u32 v[26:27], s[14:15], v72, s1, v[42:43]
	v_mad_u64_u32 v[28:29], s[14:15], v68, s1, v[42:43]
	v_mad_u64_u32 v[30:31], s[14:15], v64, s1, v[42:43]
	global_load_dwordx2 v[102:103], v[24:25], off offset:3072
	global_load_dwordx2 v[74:75], v[26:27], off offset:3072
	global_load_dwordx2 v[70:71], v[28:29], off offset:3072
	global_load_dwordx2 v[66:67], v[30:31], off offset:3072
	v_add_u32_e32 v60, 0xffff0040, v32
	v_add_u32_e32 v56, 0xffff0050, v32
	v_add_u32_e32 v50, 0xffff0060, v32
	v_add_u32_e32 v46, 0xffff0070, v32
	v_mad_u64_u32 v[24:25], s[14:15], v60, s1, v[42:43]
	v_mad_u64_u32 v[26:27], s[14:15], v56, s1, v[42:43]
	v_mad_u64_u32 v[28:29], s[14:15], v50, s1, v[42:43]
	v_mad_u64_u32 v[30:31], s[14:15], v46, s1, v[42:43]
	s_lshl_b32 s14, s10, 1
	global_load_dwordx2 v[62:63], v[24:25], off offset:3072
	global_load_dwordx2 v[58:59], v[26:27], off offset:3072
	global_load_dwordx2 v[54:55], v[28:29], off offset:3072
	global_load_dwordx2 v[48:49], v[30:31], off offset:3072
	s_add_i32 s24, s24, s14
	v_lshlrev_b32_e32 v24, 1, v76
	s_waitcnt lgkmcnt(0)
	s_barrier
	v_add3_u32 v47, s24, v24, v89
	ds_read_u16 v24, v47 offset:544
	ds_read_u16 v25, v47 offset:816
	ds_read_u16 v26, v47 offset:1088
	ds_read_u16 v27, v47 offset:1632
	ds_read_u16 v32, v47 offset:1904
	ds_read_u16 v33, v47 offset:1360
	ds_read_u16 v34, v47
	ds_read_u16 v35, v47 offset:272
	ds_read_b128 v[28:31], v92
	s_waitcnt lgkmcnt(4)
	v_perm_b32 v27, v32, v27, s63
	s_waitcnt lgkmcnt(3)
	v_perm_b32 v26, v33, v26, s63
	v_perm_b32 v25, v25, v24, s63
	s_waitcnt lgkmcnt(1)
	v_perm_b32 v24, v35, v34, s63
	ds_read_u16 v51, v47 offset:8704
	ds_read_u16 v52, v47 offset:8976
	ds_read_u16 v53, v47 offset:9792
	ds_read_u16 v57, v47 offset:10064
	ds_read_u16 v61, v47 offset:10336
	ds_read_u16 v65, v47 offset:10608
	ds_read_u16 v69, v47 offset:9248
	ds_read_u16 v73, v47 offset:9520
	ds_read_b128 v[32:35], v92 offset:64
	s_waitcnt lgkmcnt(9)
	v_mfma_f32_16x16x32_bf16 v[36:39], v[24:27], v[28:31], 0
	s_waitcnt lgkmcnt(3)
	v_perm_b32 v31, v65, v61, s63
	v_perm_b32 v30, v57, v53, s63
	s_waitcnt lgkmcnt(1)
	v_perm_b32 v29, v73, v69, s63
	v_perm_b32 v28, v52, v51, s63
	ds_read_u16 v51, v47 offset:17408
	ds_read_u16 v52, v47 offset:17680
	ds_read_u16 v53, v47 offset:18496
	ds_read_u16 v57, v47 offset:18768
	ds_read_u16 v61, v47 offset:19040
	ds_read_u16 v65, v47 offset:19312
	ds_read_u16 v69, v47 offset:17952
	ds_read_u16 v73, v47 offset:18224
	s_waitcnt lgkmcnt(8)
	v_mfma_f32_16x16x32_bf16 v[36:39], v[28:31], v[32:35], v[36:39]
	ds_read_b128 v[94:97], v92 offset:128
	s_waitcnt lgkmcnt(3)
	v_perm_b32 v35, v65, v61, s63
	v_perm_b32 v34, v57, v53, s63
	s_waitcnt lgkmcnt(1)
	v_perm_b32 v33, v73, v69, s63
	v_perm_b32 v32, v52, v51, s63
	ds_read_u16 v51, v47 offset:26112
	ds_read_u16 v52, v47 offset:26384
	ds_read_u16 v53, v47 offset:27200
	ds_read_u16 v57, v47 offset:27472
	ds_read_u16 v61, v47 offset:27744
	ds_read_u16 v65, v47 offset:28016
	ds_read_u16 v69, v47 offset:26656
	ds_read_u16 v47, v47 offset:26928
	ds_read_b128 v[98:101], v92 offset:192
	s_waitcnt lgkmcnt(9)
	v_mfma_f32_16x16x32_bf16 v[94:97], v[32:35], v[94:97], v[36:39]
	s_waitcnt lgkmcnt(5)
	s_nop 1
	v_perm_b32 v38, v57, v53, s63
	v_perm_b32 v36, v52, v51, s63
	s_waitcnt lgkmcnt(3)
	v_perm_b32 v39, v65, v61, s63
	s_waitcnt lgkmcnt(1)
	v_perm_b32 v37, v47, v69, s63
	v_lshlrev_b64 v[108:109], 11, v[152:153]
	v_mov_b32_e32 v73, v153
	s_waitcnt lgkmcnt(0)
	v_mfma_f32_16x16x32_bf16 v[94:97], v[36:39], v[98:101], v[94:97]
	v_mov_b32_e32 v69, v153
	s_xor_b32 s13, s13, 1
	s_addk_i32 s12, 0x80
	s_nop 4
	v_add_f32_e32 v65, v77, v94
	s_add_i32 s11, s11, 1
	s_cmpk_lg_i32 s12, 0x200
	s_waitcnt vmcnt(7)
	v_lshlrev_b32_e32 v104, 16, v102
	v_and_b32_e32 v105, 0xffff0000, v102
	v_and_b32_e32 v53, 0x7fffffff, v105
	v_and_b32_e32 v52, 0x7fffffff, v104
	v_pk_fma_f32 v[52:53], v[52:53], s[78:79], 1.0 op_sel_hi:[1,0,0]
	v_pk_mul_f32 v[100:101], v[104:105], v[104:105]
	v_rcp_f32_e32 v106, v52
	v_rcp_f32_e32 v107, v53
	v_mov_b64_e32 v[52:53], s[66:67]
	v_pk_mul_f32 v[100:101], v[100:101], s[68:69] op_sel_hi:[1,0]
	v_lshlrev_b32_e32 v102, 16, v103
	v_pk_fma_f32 v[98:99], v[106:107], s[74:75], v[52:53] op_sel_hi:[1,0,0]
	v_exp_f32_e32 v100, v100
	v_pk_fma_f32 v[98:99], v[106:107], v[98:99], s[62:63] op_sel_hi:[1,1,0]
	v_exp_f32_e32 v101, v101
	v_pk_fma_f32 v[98:99], v[106:107], v[98:99], s[0:1] op_sel_hi:[1,1,0]
	v_and_b32_e32 v103, 0xffff0000, v103
	v_pk_fma_f32 v[98:99], v[106:107], v[98:99], s[90:91] op_sel_hi:[1,1,0]
	v_cmp_gt_f32_e32 vcc, 0, v104
	v_pk_mul_f32 v[98:99], v[106:107], v[98:99]
	v_and_b32_e32 v107, 0x7fffffff, v103
	v_and_b32_e32 v106, 0x7fffffff, v102
	v_pk_fma_f32 v[106:107], v[106:107], s[78:79], 1.0 op_sel_hi:[1,0,0]
	v_pk_mul_f32 v[98:99], v[100:101], v[98:99]
	v_rcp_f32_e32 v106, v106
	v_rcp_f32_e32 v107, v107
	v_pk_mul_f32 v[100:101], v[104:105], v[98:99]
	v_pk_fma_f32 v[98:99], v[104:105], v[98:99], v[104:105] neg_lo:[1,0,0] neg_hi:[1,0,0]
	s_nop 0
	v_cndmask_b32_e32 v47, v98, v100, vcc
	v_cmp_gt_f32_e32 vcc, 0, v105
	v_mul_f32_e32 v47, v47, v65
	v_add_f32_e32 v65, v77, v95
	v_cndmask_b32_e32 v51, v99, v101, vcc
	v_pk_mul_f32 v[100:101], v[102:103], v[102:103]
	v_pk_fma_f32 v[98:99], v[106:107], s[74:75], v[52:53] op_sel_hi:[1,0,0]
	v_pk_mul_f32 v[100:101], v[100:101], s[68:69] op_sel_hi:[1,0]
	v_pk_fma_f32 v[98:99], v[106:107], v[98:99], s[62:63] op_sel_hi:[1,1,0]
	v_exp_f32_e32 v100, v100
	v_exp_f32_e32 v101, v101
	v_pk_fma_f32 v[98:99], v[106:107], v[98:99], s[0:1] op_sel_hi:[1,1,0]
	v_cmp_gt_f32_e32 vcc, 0, v102
	v_pk_fma_f32 v[98:99], v[106:107], v[98:99], s[90:91] op_sel_hi:[1,1,0]
	v_mul_f32_e32 v51, v51, v65
	v_pk_mul_f32 v[98:99], v[106:107], v[98:99]
	v_cvt_pk_bf16_f32 v106, v47, v51
	v_add_f32_e32 v47, v77, v96
	v_pk_mul_f32 v[98:99], v[100:101], v[98:99]
	v_add_f32_e32 v51, v77, v97
	v_pk_mul_f32 v[100:101], v[102:103], v[98:99]
	v_pk_fma_f32 v[98:99], v[102:103], v[98:99], v[102:103] neg_lo:[1,0,0] neg_hi:[1,0,0]
	s_nop 0
	v_cndmask_b32_e32 v57, v98, v100, vcc
	v_cmp_gt_f32_e32 vcc, 0, v103
	v_mul_f32_e32 v47, v57, v47
	s_nop 0
	v_cndmask_b32_e32 v61, v99, v101, vcc
	v_mul_f32_e32 v51, v61, v51
	v_cvt_pk_bf16_f32 v107, v47, v51
	ds_read_b128 v[94:97], v92 offset:4352
	ds_read_b128 v[98:101], v92 offset:4416
	s_waitcnt lgkmcnt(1)
; __device__ __forceinline__ unsigned cvt_pk_bf16(float lo, float hi) { unsigned r; asm volatile("v_cvt_pk_bf16_f32 %0, %1, %2" : "=v"(r) : "v"(lo), "v"(hi)); return r; }
; __device__ __forceinline__ float bflo(unsigned w) { return __uint_as_float(w << 16); }
; __device__ __forceinline__ float bfhi(unsigned w) { return __uint_as_float(w & 0xffff0000u); }
; PHASE_FN void sgu_block(const Params& p, unsigned char* lds, int l, int g, int ch0, int nch) {
;     ...
; #pragma unroll
;         for (int pb = 0; pb < 8; ++pb) {
;             f32x4 a = (f32x4){0.f, 0.f, 0.f, 0.f};
; #pragma unroll
;             for (int ks = 0; ks < 4; ++ks) { const bf16x8 bf = *(const bf16x8*)(wl + (16 * pb + lr) * SP + 32 * ks + 8 * q4); a = __builtin_amdgcn_mfma_f32_16x16x32_bf16(af[ks], bf, a, 0, 0, 0); }
;             const f32x2 u0 = gelu_pk((f32x2){bflo(uw[pb].x), bfhi(uw[pb].x)}), u1 = gelu_pk((f32x2){bflo(uw[pb].y), bfhi(uw[pb].y)});
;             u32x2 w; w.x = cvt_pk_bf16((a[0] + bs[pb]) * u0.x, (a[1] + bs[pb]) * u0.y); w.y = cvt_pk_bf16((a[2] + bs[pb]) * u1.x, (a[3] + bs[pb]) * u1.y);
;             *(u32x2*)(MIX + (size_t)(tok0 + 16 * pb + lr) * D + 512 + ocol) = w;
;         }
	v_mfma_f32_16x16x32_bf16 v[94:97], v[24:27], v[94:97], 0
	ds_read_b128 v[102:105], v92 offset:4480
	s_waitcnt lgkmcnt(1)
	v_mfma_f32_16x16x32_bf16 v[94:97], v[28:31], v[98:101], v[94:97]
	v_lshl_add_u64 v[98:99], s[86:87], 0, v[108:109]
	v_lshl_add_u64 v[108:109], v[98:99], 0, v[44:45]
	ds_read_b128 v[98:101], v92 offset:4544
	s_waitcnt lgkmcnt(1)
	v_mfma_f32_16x16x32_bf16 v[94:97], v[32:35], v[102:105], v[94:97]
	s_waitcnt vmcnt(6)
	v_lshlrev_b32_e32 v102, 16, v74
	v_and_b32_e32 v103, 0xffff0000, v74
	v_and_b32_e32 v105, 0x7fffffff, v103
	v_and_b32_e32 v104, 0x7fffffff, v102
	v_pk_fma_f32 v[104:105], v[104:105], s[78:79], 1.0 op_sel_hi:[1,0,0]
	s_waitcnt lgkmcnt(0)
	v_mfma_f32_16x16x32_bf16 v[94:97], v[36:39], v[98:101], v[94:97]
	v_rcp_f32_e32 v104, v104
	v_rcp_f32_e32 v105, v105
	v_pk_mul_f32 v[100:101], v[102:103], v[102:103]
	v_lshlrev_b32_e32 v74, 16, v75
	v_pk_mul_f32 v[100:101], v[100:101], s[68:69] op_sel_hi:[1,0]
	v_pk_fma_f32 v[98:99], v[104:105], s[74:75], v[52:53] op_sel_hi:[1,0,0]
	v_exp_f32_e32 v100, v100
	v_pk_fma_f32 v[98:99], v[104:105], v[98:99], s[62:63] op_sel_hi:[1,1,0]
	v_exp_f32_e32 v101, v101
	v_pk_fma_f32 v[98:99], v[104:105], v[98:99], s[0:1] op_sel_hi:[1,1,0]
	v_and_b32_e32 v75, 0xffff0000, v75
	v_pk_fma_f32 v[98:99], v[104:105], v[98:99], s[90:91] op_sel_hi:[1,1,0]
	v_add_co_u32_e32 v108, vcc, s33, v108
	v_pk_mul_f32 v[98:99], v[104:105], v[98:99]
	v_and_b32_e32 v105, 0x7fffffff, v75
	v_and_b32_e32 v104, 0x7fffffff, v74
	v_pk_fma_f32 v[104:105], v[104:105], s[78:79], 1.0 op_sel_hi:[1,0,0]
	v_addc_co_u32_e32 v109, vcc, 0, v109, vcc
	v_pk_mul_f32 v[98:99], v[100:101], v[98:99]
	v_rcp_f32_e32 v104, v104
	v_rcp_f32_e32 v105, v105
	v_pk_mul_f32 v[100:101], v[102:103], v[98:99]
	v_pk_fma_f32 v[98:99], v[102:103], v[98:99], v[102:103] neg_lo:[1,0,0] neg_hi:[1,0,0]
	v_cmp_gt_f32_e32 vcc, 0, v102
	v_add_f32_e32 v65, v78, v94
	global_store_dwordx2 v[108:109], v[106:107], off offset:1024 nt
	v_cndmask_b32_e32 v47, v98, v100, vcc
	v_cmp_gt_f32_e32 vcc, 0, v103
	v_mul_f32_e32 v47, v47, v65
	v_add_f32_e32 v65, v78, v95
	v_cndmask_b32_e32 v51, v99, v101, vcc
	v_pk_mul_f32 v[100:101], v[74:75], v[74:75]
	v_pk_fma_f32 v[98:99], v[104:105], s[74:75], v[52:53] op_sel_hi:[1,0,0]
	v_pk_mul_f32 v[100:101], v[100:101], s[68:69] op_sel_hi:[1,0]
	v_pk_fma_f32 v[98:99], v[104:105], v[98:99], s[62:63] op_sel_hi:[1,1,0]
	v_exp_f32_e32 v100, v100
	v_exp_f32_e32 v101, v101
	v_pk_fma_f32 v[98:99], v[104:105], v[98:99], s[0:1] op_sel_hi:[1,1,0]
	v_cmp_gt_f32_e32 vcc, 0, v74
	v_pk_fma_f32 v[98:99], v[104:105], v[98:99], s[90:91] op_sel_hi:[1,1,0]
	v_mul_f32_e32 v51, v51, v65
	v_pk_mul_f32 v[98:99], v[104:105], v[98:99]
	v_cvt_pk_bf16_f32 v102, v47, v51
	v_add_f32_e32 v47, v78, v96
	v_pk_mul_f32 v[98:99], v[100:101], v[98:99]
	v_add_f32_e32 v51, v78, v97
	v_pk_mul_f32 v[100:101], v[74:75], v[98:99]
	v_pk_fma_f32 v[98:99], v[74:75], v[98:99], v[74:75] neg_lo:[1,0,0] neg_hi:[1,0,0]
	v_lshlrev_b64 v[104:105], 11, v[72:73]
	v_cndmask_b32_e32 v57, v98, v100, vcc
	v_cmp_gt_f32_e32 vcc, 0, v75
	v_mul_f32_e32 v47, v57, v47
	s_nop 0
	v_cndmask_b32_e32 v61, v99, v101, vcc
	v_mul_f32_e32 v51, v61, v51
	v_cvt_pk_bf16_f32 v103, v47, v51
	ds_read_b128 v[94:97], v92 offset:8704
	ds_read_b128 v[98:101], v92 offset:8768
	s_waitcnt lgkmcnt(1)
	v_mfma_f32_16x16x32_bf16 v[94:97], v[24:27], v[94:97], 0
	ds_read_b128 v[72:75], v92 offset:8832
	s_waitcnt lgkmcnt(1)
	v_mfma_f32_16x16x32_bf16 v[94:97], v[28:31], v[98:101], v[94:97]
	v_lshl_add_u64 v[98:99], s[86:87], 0, v[104:105]
	v_lshl_add_u64 v[104:105], v[98:99], 0, v[44:45]
	ds_read_b128 v[98:101], v92 offset:8896
	s_waitcnt lgkmcnt(1)
	v_mfma_f32_16x16x32_bf16 v[72:75], v[32:35], v[72:75], v[94:97]
	v_add_co_u32_e32 v104, vcc, s33, v104
	s_waitcnt vmcnt(6)
	s_nop 0
	v_lshlrev_b32_e32 v94, 16, v70
	v_and_b32_e32 v95, 0xffff0000, v70
	v_and_b32_e32 v97, 0x7fffffff, v95
	v_and_b32_e32 v96, 0x7fffffff, v94
	v_pk_fma_f32 v[96:97], v[96:97], s[78:79], 1.0 op_sel_hi:[1,0,0]
	s_waitcnt lgkmcnt(0)
	v_mfma_f32_16x16x32_bf16 v[72:75], v[36:39], v[98:101], v[72:75]
	v_rcp_f32_e32 v96, v96
	v_rcp_f32_e32 v97, v97
	v_pk_mul_f32 v[100:101], v[94:95], v[94:95]
	v_lshlrev_b32_e32 v70, 16, v71
	v_pk_mul_f32 v[100:101], v[100:101], s[68:69] op_sel_hi:[1,0]
	v_pk_fma_f32 v[98:99], v[96:97], s[74:75], v[52:53] op_sel_hi:[1,0,0]
	v_exp_f32_e32 v100, v100
	v_pk_fma_f32 v[98:99], v[96:97], v[98:99], s[62:63] op_sel_hi:[1,1,0]
	v_exp_f32_e32 v101, v101
	v_pk_fma_f32 v[98:99], v[96:97], v[98:99], s[0:1] op_sel_hi:[1,1,0]
	v_and_b32_e32 v71, 0xffff0000, v71
	v_pk_fma_f32 v[98:99], v[96:97], v[98:99], s[90:91] op_sel_hi:[1,1,0]
	v_addc_co_u32_e32 v105, vcc, 0, v105, vcc
	v_pk_mul_f32 v[96:97], v[96:97], v[98:99]
	v_cmp_gt_f32_e32 vcc, 0, v94
	v_pk_mul_f32 v[96:97], v[100:101], v[96:97]
	v_and_b32_e32 v101, 0x7fffffff, v71
	v_and_b32_e32 v100, 0x7fffffff, v70
	v_pk_fma_f32 v[100:101], v[100:101], s[78:79], 1.0 op_sel_hi:[1,0,0]
	v_pk_mul_f32 v[98:99], v[94:95], v[96:97]
	v_rcp_f32_e32 v100, v100
	v_rcp_f32_e32 v101, v101
	v_pk_fma_f32 v[96:97], v[94:95], v[96:97], v[94:95] neg_lo:[1,0,0] neg_hi:[1,0,0]
	v_add_f32_e32 v65, v79, v72
	v_cndmask_b32_e32 v47, v96, v98, vcc
	v_cmp_gt_f32_e32 vcc, 0, v95
	v_pk_fma_f32 v[94:95], v[100:101], s[74:75], v[52:53] op_sel_hi:[1,0,0]
	v_mul_f32_e32 v47, v47, v65
	v_cndmask_b32_e32 v51, v97, v99, vcc
	v_pk_mul_f32 v[96:97], v[70:71], v[70:71]
	v_pk_fma_f32 v[94:95], v[100:101], v[94:95], s[62:63] op_sel_hi:[1,1,0]
	v_pk_mul_f32 v[96:97], v[96:97], s[68:69] op_sel_hi:[1,0]
	v_pk_fma_f32 v[94:95], v[100:101], v[94:95], s[0:1] op_sel_hi:[1,1,0]
	v_exp_f32_e32 v96, v96
	v_exp_f32_e32 v97, v97
	v_pk_fma_f32 v[94:95], v[100:101], v[94:95], s[90:91] op_sel_hi:[1,1,0]
	v_cmp_gt_f32_e32 vcc, 0, v70
	v_pk_mul_f32 v[94:95], v[100:101], v[94:95]
	v_add_f32_e32 v65, v79, v73
	v_pk_mul_f32 v[94:95], v[96:97], v[94:95]
	v_mul_f32_e32 v51, v51, v65
	v_pk_mul_f32 v[96:97], v[70:71], v[94:95]
	v_pk_fma_f32 v[94:95], v[70:71], v[94:95], v[70:71] neg_lo:[1,0,0] neg_hi:[1,0,0]
	global_store_dwordx2 v[104:105], v[102:103], off offset:1024 nt
	v_cndmask_b32_e32 v57, v94, v96, vcc
	v_cmp_gt_f32_e32 vcc, 0, v71
	v_cvt_pk_bf16_f32 v102, v47, v51
	v_add_f32_e32 v47, v79, v74
	v_add_f32_e32 v51, v79, v75
	v_cndmask_b32_e32 v61, v95, v97, vcc
	v_mul_f32_e32 v47, v57, v47
	v_mul_f32_e32 v51, v61, v51
	v_cvt_pk_bf16_f32 v103, v47, v51
	ds_read_b128 v[70:73], v92 offset:13056
	ds_read_b128 v[94:97], v92 offset:13120
	s_waitcnt lgkmcnt(1)
; __device__ __forceinline__ unsigned cvt_pk_bf16(float lo, float hi) { unsigned r; asm volatile("v_cvt_pk_bf16_f32 %0, %1, %2" : "=v"(r) : "v"(lo), "v"(hi)); return r; }
; __device__ __forceinline__ float bflo(unsigned w) { return __uint_as_float(w << 16); }
; __device__ __forceinline__ float bfhi(unsigned w) { return __uint_as_float(w & 0xffff0000u); }
; PHASE_FN void sgu_block(const Params& p, unsigned char* lds, int l, int g, int ch0, int nch) {
;     ...
; #pragma unroll
;         for (int pb = 0; pb < 8; ++pb) {
;             f32x4 a = (f32x4){0.f, 0.f, 0.f, 0.f};
; #pragma unroll
;             for (int ks = 0; ks < 4; ++ks) { const bf16x8 bf = *(const bf16x8*)(wl + (16 * pb + lr) * SP + 32 * ks + 8 * q4); a = __builtin_amdgcn_mfma_f32_16x16x32_bf16(af[ks], bf, a, 0, 0, 0); }
;             const f32x2 u0 = gelu_pk((f32x2){bflo(uw[pb].x), bfhi(uw[pb].x)}), u1 = gelu_pk((f32x2){bflo(uw[pb].y), bfhi(uw[pb].y)});
;             u32x2 w; w.x = cvt_pk_bf16((a[0] + bs[pb]) * u0.x, (a[1] + bs[pb]) * u0.y); w.y = cvt_pk_bf16((a[2] + bs[pb]) * u1.x, (a[3] + bs[pb]) * u1.y);
;             *(u32x2*)(MIX + (size_t)(tok0 + 16 * pb + lr) * D + 512 + ocol) = w;
;         }
	v_mfma_f32_16x16x32_bf16 v[70:73], v[24:27], v[70:73], 0
	ds_read_b128 v[98:101], v92 offset:13184
	v_lshlrev_b64 v[74:75], 11, v[68:69]
	s_waitcnt lgkmcnt(1)
	v_mfma_f32_16x16x32_bf16 v[68:71], v[28:31], v[94:97], v[70:73]
	s_waitcnt vmcnt(6)
	v_lshlrev_b32_e32 v96, 16, v66
	v_and_b32_e32 v97, 0xffff0000, v66
	v_lshlrev_b32_e32 v66, 16, v67
	v_lshl_add_u64 v[72:73], s[86:87], 0, v[74:75]
	v_lshl_add_u64 v[94:95], v[72:73], 0, v[44:45]
	ds_read_b128 v[72:75], v92 offset:13248
	s_waitcnt lgkmcnt(1)
	v_mfma_f32_16x16x32_bf16 v[68:71], v[32:35], v[98:101], v[68:71]
	v_and_b32_e32 v99, 0x7fffffff, v97
	v_and_b32_e32 v98, 0x7fffffff, v96
	v_pk_fma_f32 v[98:99], v[98:99], s[78:79], 1.0 op_sel_hi:[1,0,0]
	s_waitcnt lgkmcnt(0)
	v_mfma_f32_16x16x32_bf16 v[68:71], v[36:39], v[72:75], v[68:71]
	v_rcp_f32_e32 v98, v98
	v_rcp_f32_e32 v99, v99
	v_pk_mul_f32 v[74:75], v[96:97], v[96:97]
	v_add_co_u32_e32 v94, vcc, s33, v94
	v_pk_fma_f32 v[72:73], v[98:99], s[74:75], v[52:53] op_sel_hi:[1,0,0]
	v_pk_mul_f32 v[74:75], v[74:75], s[68:69] op_sel_hi:[1,0]
	v_pk_fma_f32 v[72:73], v[98:99], v[72:73], s[62:63] op_sel_hi:[1,1,0]
	v_exp_f32_e32 v74, v74
	v_exp_f32_e32 v75, v75
	v_addc_co_u32_e32 v95, vcc, 0, v95, vcc
	v_pk_fma_f32 v[72:73], v[98:99], v[72:73], s[0:1] op_sel_hi:[1,1,0]
	v_and_b32_e32 v67, 0xffff0000, v67
	global_store_dwordx2 v[94:95], v[102:103], off offset:1024 nt
	v_pk_fma_f32 v[72:73], v[98:99], v[72:73], s[90:91] op_sel_hi:[1,1,0]
	v_and_b32_e32 v95, 0x7fffffff, v67
	v_and_b32_e32 v94, 0x7fffffff, v66
	v_pk_mul_f32 v[72:73], v[98:99], v[72:73]
	v_pk_fma_f32 v[94:95], v[94:95], s[78:79], 1.0 op_sel_hi:[1,0,0]
	v_pk_mul_f32 v[72:73], v[74:75], v[72:73]
	v_rcp_f32_e32 v94, v94
	v_rcp_f32_e32 v95, v95
	v_pk_mul_f32 v[74:75], v[96:97], v[72:73]
	v_pk_fma_f32 v[72:73], v[96:97], v[72:73], v[96:97] neg_lo:[1,0,0] neg_hi:[1,0,0]
	v_cmp_gt_f32_e32 vcc, 0, v96
	v_add_f32_e32 v65, v80, v68
	s_nop 0
	v_cndmask_b32_e32 v47, v72, v74, vcc
	v_cmp_gt_f32_e32 vcc, 0, v97
	v_mul_f32_e32 v47, v47, v65
	v_add_f32_e32 v65, v80, v69
	v_cndmask_b32_e32 v51, v73, v75, vcc
	v_pk_mul_f32 v[74:75], v[66:67], v[66:67]
	v_pk_fma_f32 v[72:73], v[94:95], s[74:75], v[52:53] op_sel_hi:[1,0,0]
	v_pk_mul_f32 v[74:75], v[74:75], s[68:69] op_sel_hi:[1,0]
	v_pk_fma_f32 v[72:73], v[94:95], v[72:73], s[62:63] op_sel_hi:[1,1,0]
	v_exp_f32_e32 v74, v74
	v_exp_f32_e32 v75, v75
	v_pk_fma_f32 v[72:73], v[94:95], v[72:73], s[0:1] op_sel_hi:[1,1,0]
	v_cmp_gt_f32_e32 vcc, 0, v66
	v_pk_fma_f32 v[72:73], v[94:95], v[72:73], s[90:91] op_sel_hi:[1,1,0]
	v_mul_f32_e32 v51, v51, v65
	v_pk_mul_f32 v[72:73], v[94:95], v[72:73]
	v_mov_b32_e32 v65, v153
	v_pk_mul_f32 v[72:73], v[74:75], v[72:73]
	v_lshlrev_b64 v[98:99], 11, v[64:65]
	v_pk_mul_f32 v[74:75], v[66:67], v[72:73]
	v_pk_fma_f32 v[72:73], v[66:67], v[72:73], v[66:67] neg_lo:[1,0,0] neg_hi:[1,0,0]
	s_nop 0
	v_cndmask_b32_e32 v57, v72, v74, vcc
	v_cmp_gt_f32_e32 vcc, 0, v67
	v_cvt_pk_bf16_f32 v74, v47, v51
	v_add_f32_e32 v47, v80, v70
	v_add_f32_e32 v51, v80, v71
	v_cndmask_b32_e32 v61, v73, v75, vcc
	v_mul_f32_e32 v47, v57, v47
	v_mul_f32_e32 v51, v61, v51
	v_cvt_pk_bf16_f32 v75, v47, v51
	ds_read_b128 v[66:69], v92 offset:17408
	ds_read_b128 v[70:73], v92 offset:17472
	s_waitcnt lgkmcnt(1)
	v_mfma_f32_16x16x32_bf16 v[66:69], v[24:27], v[66:69], 0
	ds_read_b128 v[94:97], v92 offset:17536
	s_waitcnt lgkmcnt(1)
	v_mfma_f32_16x16x32_bf16 v[64:67], v[28:31], v[70:73], v[66:69]
	s_nop 4
	v_lshl_add_u64 v[68:69], s[86:87], 0, v[98:99]
	v_lshl_add_u64 v[72:73], v[68:69], 0, v[44:45]
	ds_read_b128 v[68:71], v92 offset:17600
	s_waitcnt lgkmcnt(1)
	v_mfma_f32_16x16x32_bf16 v[64:67], v[32:35], v[94:97], v[64:67]
	s_waitcnt vmcnt(6)
	v_lshlrev_b32_e32 v94, 16, v62
	v_and_b32_e32 v95, 0xffff0000, v62
	v_and_b32_e32 v97, 0x7fffffff, v95
	v_and_b32_e32 v96, 0x7fffffff, v94
	v_pk_fma_f32 v[96:97], v[96:97], s[78:79], 1.0 op_sel_hi:[1,0,0]
	s_waitcnt lgkmcnt(0)
	v_mfma_f32_16x16x32_bf16 v[64:67], v[36:39], v[68:71], v[64:67]
	v_rcp_f32_e32 v96, v96
	v_rcp_f32_e32 v97, v97
	v_pk_mul_f32 v[70:71], v[94:95], v[94:95]
	v_add_co_u32_e32 v72, vcc, s33, v72
	v_pk_fma_f32 v[68:69], v[96:97], s[74:75], v[52:53] op_sel_hi:[1,0,0]
	v_pk_mul_f32 v[70:71], v[70:71], s[68:69] op_sel_hi:[1,0]
	v_pk_fma_f32 v[68:69], v[96:97], v[68:69], s[62:63] op_sel_hi:[1,1,0]
	v_exp_f32_e32 v70, v70
	v_exp_f32_e32 v71, v71
	v_addc_co_u32_e32 v73, vcc, 0, v73, vcc
	v_pk_fma_f32 v[68:69], v[96:97], v[68:69], s[0:1] op_sel_hi:[1,1,0]
	v_lshlrev_b32_e32 v62, 16, v63
	v_and_b32_e32 v63, 0xffff0000, v63
	global_store_dwordx2 v[72:73], v[74:75], off offset:1024 nt
	v_pk_fma_f32 v[68:69], v[96:97], v[68:69], s[90:91] op_sel_hi:[1,1,0]
	v_and_b32_e32 v73, 0x7fffffff, v63
	v_and_b32_e32 v72, 0x7fffffff, v62
	v_pk_mul_f32 v[68:69], v[96:97], v[68:69]
	v_pk_fma_f32 v[72:73], v[72:73], s[78:79], 1.0 op_sel_hi:[1,0,0]
	v_pk_mul_f32 v[68:69], v[70:71], v[68:69]
	v_rcp_f32_e32 v72, v72
	v_rcp_f32_e32 v73, v73
	v_pk_mul_f32 v[70:71], v[94:95], v[68:69]
	v_pk_fma_f32 v[68:69], v[94:95], v[68:69], v[94:95] neg_lo:[1,0,0] neg_hi:[1,0,0]
	v_cmp_gt_f32_e32 vcc, 0, v94
	s_nop 1
	v_cndmask_b32_e32 v47, v68, v70, vcc
	v_cmp_gt_f32_e32 vcc, 0, v95
	s_nop 1
	v_cndmask_b32_e32 v51, v69, v71, vcc
	v_pk_mul_f32 v[70:71], v[62:63], v[62:63]
	v_pk_fma_f32 v[68:69], v[72:73], s[74:75], v[52:53] op_sel_hi:[1,0,0]
	v_pk_mul_f32 v[70:71], v[70:71], s[68:69] op_sel_hi:[1,0]
	v_pk_fma_f32 v[68:69], v[72:73], v[68:69], s[62:63] op_sel_hi:[1,1,0]
	v_exp_f32_e32 v70, v70
	v_exp_f32_e32 v71, v71
	v_pk_fma_f32 v[68:69], v[72:73], v[68:69], s[0:1] op_sel_hi:[1,1,0]
	v_cmp_gt_f32_e32 vcc, 0, v62
	v_pk_fma_f32 v[68:69], v[72:73], v[68:69], s[90:91] op_sel_hi:[1,1,0]
	s_nop 0
	v_pk_mul_f32 v[68:69], v[72:73], v[68:69]
	s_nop 0
	v_pk_mul_f32 v[68:69], v[70:71], v[68:69]
	s_nop 0
	v_pk_mul_f32 v[70:71], v[62:63], v[68:69]
	v_pk_fma_f32 v[68:69], v[62:63], v[68:69], v[62:63] neg_lo:[1,0,0] neg_hi:[1,0,0]
	v_add_f32_e32 v62, v81, v64
	v_mul_f32_e32 v47, v47, v62
	v_add_f32_e32 v62, v81, v65
	v_cndmask_b32_e32 v57, v68, v70, vcc
	v_cmp_gt_f32_e32 vcc, 0, v63
	v_mul_f32_e32 v51, v51, v62
	v_cvt_pk_bf16_f32 v74, v47, v51
	v_add_f32_e32 v47, v81, v66
	v_cndmask_b32_e32 v61, v69, v71, vcc
	v_add_f32_e32 v51, v81, v67
	v_mul_f32_e32 v47, v57, v47
	v_mul_f32_e32 v51, v61, v51
	v_cvt_pk_bf16_f32 v75, v47, v51
	ds_read_b128 v[62:65], v92 offset:21760
	ds_read_b128 v[66:69], v92 offset:21824
	s_waitcnt lgkmcnt(1)
; __device__ __forceinline__ unsigned cvt_pk_bf16(float lo, float hi) { unsigned r; asm volatile("v_cvt_pk_bf16_f32 %0, %1, %2" : "=v"(r) : "v"(lo), "v"(hi)); return r; }
; __device__ __forceinline__ float bflo(unsigned w) { return __uint_as_float(w << 16); }
; __device__ __forceinline__ float bfhi(unsigned w) { return __uint_as_float(w & 0xffff0000u); }
; PHASE_FN void sgu_block(const Params& p, unsigned char* lds, int l, int g, int ch0, int nch) {
;     ...
; #pragma unroll
;         for (int pb = 0; pb < 8; ++pb) {
;             f32x4 a = (f32x4){0.f, 0.f, 0.f, 0.f};
; #pragma unroll
;             for (int ks = 0; ks < 4; ++ks) { const bf16x8 bf = *(const bf16x8*)(wl + (16 * pb + lr) * SP + 32 * ks + 8 * q4); a = __builtin_amdgcn_mfma_f32_16x16x32_bf16(af[ks], bf, a, 0, 0, 0); }
;             const f32x2 u0 = gelu_pk((f32x2){bflo(uw[pb].x), bfhi(uw[pb].x)}), u1 = gelu_pk((f32x2){bflo(uw[pb].y), bfhi(uw[pb].y)});
;             u32x2 w; w.x = cvt_pk_bf16((a[0] + bs[pb]) * u0.x, (a[1] + bs[pb]) * u0.y); w.y = cvt_pk_bf16((a[2] + bs[pb]) * u1.x, (a[3] + bs[pb]) * u1.y);
;             *(u32x2*)(MIX + (size_t)(tok0 + 16 * pb + lr) * D + 512 + ocol) = w;
;         }
	v_mfma_f32_16x16x32_bf16 v[62:65], v[24:27], v[62:65], 0
	v_mov_b32_e32 v61, v153
	ds_read_b128 v[70:73], v92 offset:21888
	v_lshlrev_b64 v[94:95], 11, v[60:61]
	s_waitcnt lgkmcnt(1)
	v_mfma_f32_16x16x32_bf16 v[60:63], v[28:31], v[66:69], v[62:65]
	s_nop 2
	v_lshl_add_u64 v[64:65], s[86:87], 0, v[94:95]
	v_lshl_add_u64 v[68:69], v[64:65], 0, v[44:45]
	ds_read_b128 v[64:67], v92 offset:21952
	s_waitcnt lgkmcnt(1)
	v_mfma_f32_16x16x32_bf16 v[60:63], v[32:35], v[70:73], v[60:63]
	s_waitcnt vmcnt(6)
	v_lshlrev_b32_e32 v70, 16, v58
	v_and_b32_e32 v71, 0xffff0000, v58
	v_and_b32_e32 v73, 0x7fffffff, v71
	v_and_b32_e32 v72, 0x7fffffff, v70
	v_pk_fma_f32 v[72:73], v[72:73], s[78:79], 1.0 op_sel_hi:[1,0,0]
	s_waitcnt lgkmcnt(0)
	v_mfma_f32_16x16x32_bf16 v[60:63], v[36:39], v[64:67], v[60:63]
	v_rcp_f32_e32 v72, v72
	v_rcp_f32_e32 v73, v73
	v_pk_mul_f32 v[66:67], v[70:71], v[70:71]
	v_add_co_u32_e32 v68, vcc, s33, v68
	v_pk_fma_f32 v[64:65], v[72:73], s[74:75], v[52:53] op_sel_hi:[1,0,0]
	v_pk_mul_f32 v[66:67], v[66:67], s[68:69] op_sel_hi:[1,0]
	v_pk_fma_f32 v[64:65], v[72:73], v[64:65], s[62:63] op_sel_hi:[1,1,0]
	v_exp_f32_e32 v66, v66
	v_exp_f32_e32 v67, v67
	v_addc_co_u32_e32 v69, vcc, 0, v69, vcc
	v_pk_fma_f32 v[64:65], v[72:73], v[64:65], s[0:1] op_sel_hi:[1,1,0]
	v_lshlrev_b32_e32 v58, 16, v59
	v_and_b32_e32 v59, 0xffff0000, v59
	global_store_dwordx2 v[68:69], v[74:75], off offset:1024 nt
	v_pk_fma_f32 v[64:65], v[72:73], v[64:65], s[90:91] op_sel_hi:[1,1,0]
	v_and_b32_e32 v69, 0x7fffffff, v59
	v_and_b32_e32 v68, 0x7fffffff, v58
	v_pk_mul_f32 v[64:65], v[72:73], v[64:65]
	v_pk_fma_f32 v[68:69], v[68:69], s[78:79], 1.0 op_sel_hi:[1,0,0]
	v_pk_mul_f32 v[64:65], v[66:67], v[64:65]
	v_rcp_f32_e32 v68, v68
	v_rcp_f32_e32 v69, v69
	v_pk_mul_f32 v[66:67], v[70:71], v[64:65]
	v_pk_fma_f32 v[64:65], v[70:71], v[64:65], v[70:71] neg_lo:[1,0,0] neg_hi:[1,0,0]
	v_cmp_gt_f32_e32 vcc, 0, v70
	s_nop 1
	v_cndmask_b32_e32 v47, v64, v66, vcc
	v_cmp_gt_f32_e32 vcc, 0, v71
	s_nop 1
	v_cndmask_b32_e32 v51, v65, v67, vcc
	v_pk_mul_f32 v[66:67], v[58:59], v[58:59]
	v_pk_fma_f32 v[64:65], v[68:69], s[74:75], v[52:53] op_sel_hi:[1,0,0]
	v_pk_mul_f32 v[66:67], v[66:67], s[68:69] op_sel_hi:[1,0]
	v_pk_fma_f32 v[64:65], v[68:69], v[64:65], s[62:63] op_sel_hi:[1,1,0]
	v_exp_f32_e32 v66, v66
	v_exp_f32_e32 v67, v67
	v_pk_fma_f32 v[64:65], v[68:69], v[64:65], s[0:1] op_sel_hi:[1,1,0]
	v_cmp_gt_f32_e32 vcc, 0, v58
	v_pk_fma_f32 v[64:65], v[68:69], v[64:65], s[90:91] op_sel_hi:[1,1,0]
	s_nop 0
	v_pk_mul_f32 v[64:65], v[68:69], v[64:65]
	s_nop 0
	v_pk_mul_f32 v[64:65], v[66:67], v[64:65]
	s_nop 0
	v_pk_mul_f32 v[66:67], v[58:59], v[64:65]
	v_pk_fma_f32 v[64:65], v[58:59], v[64:65], v[58:59] neg_lo:[1,0,0] neg_hi:[1,0,0]
	s_nop 0
	v_cndmask_b32_e32 v57, v64, v66, vcc
	v_cmp_gt_f32_e32 vcc, 0, v59
	v_add_f32_e32 v59, v82, v60
	v_mul_f32_e32 v47, v47, v59
	v_add_f32_e32 v59, v82, v61
	v_mul_f32_e32 v51, v51, v59
	v_cndmask_b32_e32 v58, v65, v67, vcc
	v_cvt_pk_bf16_f32 v70, v47, v51
	v_add_f32_e32 v47, v82, v62
	v_add_f32_e32 v51, v82, v63
	v_mul_f32_e32 v47, v57, v47
	v_mul_f32_e32 v51, v58, v51
	v_cvt_pk_bf16_f32 v71, v47, v51
	ds_read_b128 v[58:61], v92 offset:26112
	ds_read_b128 v[62:65], v92 offset:26176
	s_waitcnt lgkmcnt(1)
	v_mfma_f32_16x16x32_bf16 v[58:61], v[24:27], v[58:61], 0
	v_mov_b32_e32 v57, v153
	ds_read_b128 v[66:69], v92 offset:26240
	v_lshlrev_b64 v[72:73], 11, v[56:57]
	s_waitcnt lgkmcnt(1)
	v_mfma_f32_16x16x32_bf16 v[56:59], v[28:31], v[62:65], v[58:61]
	s_nop 2
	v_lshl_add_u64 v[60:61], s[86:87], 0, v[72:73]
	v_lshl_add_u64 v[64:65], v[60:61], 0, v[44:45]
	ds_read_b128 v[60:63], v92 offset:26304
	s_waitcnt lgkmcnt(1)
	v_mfma_f32_16x16x32_bf16 v[56:59], v[32:35], v[66:69], v[56:59]
	s_waitcnt vmcnt(6)
	v_lshlrev_b32_e32 v66, 16, v54
	v_and_b32_e32 v67, 0xffff0000, v54
	v_and_b32_e32 v69, 0x7fffffff, v67
	v_and_b32_e32 v68, 0x7fffffff, v66
	v_pk_fma_f32 v[68:69], v[68:69], s[78:79], 1.0 op_sel_hi:[1,0,0]
	s_waitcnt lgkmcnt(0)
; __device__ __forceinline__ unsigned cvt_pk_bf16(float lo, float hi) { unsigned r; asm volatile("v_cvt_pk_bf16_f32 %0, %1, %2" : "=v"(r) : "v"(lo), "v"(hi)); return r; }
; __device__ __forceinline__ float bflo(unsigned w) { return __uint_as_float(w << 16); }
; __device__ __forceinline__ float bfhi(unsigned w) { return __uint_as_float(w & 0xffff0000u); }
; PHASE_FN void sgu_block(const Params& p, unsigned char* lds, int l, int g, int ch0, int nch) {
;     ...
; #pragma unroll
;         for (int pb = 0; pb < 8; ++pb) {
;             f32x4 a = (f32x4){0.f, 0.f, 0.f, 0.f};
; #pragma unroll
;             for (int ks = 0; ks < 4; ++ks) { const bf16x8 bf = *(const bf16x8*)(wl + (16 * pb + lr) * SP + 32 * ks + 8 * q4); a = __builtin_amdgcn_mfma_f32_16x16x32_bf16(af[ks], bf, a, 0, 0, 0); }
;             const f32x2 u0 = gelu_pk((f32x2){bflo(uw[pb].x), bfhi(uw[pb].x)}), u1 = gelu_pk((f32x2){bflo(uw[pb].y), bfhi(uw[pb].y)});
;             u32x2 w; w.x = cvt_pk_bf16((a[0] + bs[pb]) * u0.x, (a[1] + bs[pb]) * u0.y); w.y = cvt_pk_bf16((a[2] + bs[pb]) * u1.x, (a[3] + bs[pb]) * u1.y);
;             *(u32x2*)(MIX + (size_t)(tok0 + 16 * pb + lr) * D + 512 + ocol) = w;
;         }
	v_mfma_f32_16x16x32_bf16 v[56:59], v[36:39], v[60:63], v[56:59]
	v_rcp_f32_e32 v68, v68
	v_rcp_f32_e32 v69, v69
	v_pk_mul_f32 v[62:63], v[66:67], v[66:67]
	v_add_co_u32_e32 v64, vcc, s33, v64
	v_pk_fma_f32 v[60:61], v[68:69], s[74:75], v[52:53] op_sel_hi:[1,0,0]
	v_pk_mul_f32 v[62:63], v[62:63], s[68:69] op_sel_hi:[1,0]
	v_pk_fma_f32 v[60:61], v[68:69], v[60:61], s[62:63] op_sel_hi:[1,1,0]
	v_exp_f32_e32 v62, v62
	v_exp_f32_e32 v63, v63
	v_addc_co_u32_e32 v65, vcc, 0, v65, vcc
	v_pk_fma_f32 v[60:61], v[68:69], v[60:61], s[0:1] op_sel_hi:[1,1,0]
	v_lshlrev_b32_e32 v54, 16, v55
	v_and_b32_e32 v55, 0xffff0000, v55
	global_store_dwordx2 v[64:65], v[70:71], off offset:1024 nt
	v_pk_fma_f32 v[60:61], v[68:69], v[60:61], s[90:91] op_sel_hi:[1,1,0]
	v_and_b32_e32 v65, 0x7fffffff, v55
	v_and_b32_e32 v64, 0x7fffffff, v54
	v_pk_mul_f32 v[60:61], v[68:69], v[60:61]
	v_pk_fma_f32 v[64:65], v[64:65], s[78:79], 1.0 op_sel_hi:[1,0,0]
	v_pk_mul_f32 v[60:61], v[62:63], v[60:61]
	v_rcp_f32_e32 v64, v64
	v_rcp_f32_e32 v65, v65
	v_pk_mul_f32 v[62:63], v[66:67], v[60:61]
	v_pk_fma_f32 v[60:61], v[66:67], v[60:61], v[66:67] neg_lo:[1,0,0] neg_hi:[1,0,0]
	v_cmp_gt_f32_e32 vcc, 0, v66
	v_add_f32_e32 v56, v83, v56
	s_nop 0
	v_cndmask_b32_e32 v47, v60, v62, vcc
	v_cmp_gt_f32_e32 vcc, 0, v67
	v_mul_f32_e32 v47, v47, v56
	v_add_f32_e32 v56, v83, v57
	v_cndmask_b32_e32 v51, v61, v63, vcc
	v_pk_mul_f32 v[62:63], v[54:55], v[54:55]
	v_pk_fma_f32 v[60:61], v[64:65], s[74:75], v[52:53] op_sel_hi:[1,0,0]
	v_pk_mul_f32 v[62:63], v[62:63], s[68:69] op_sel_hi:[1,0]
	v_pk_fma_f32 v[60:61], v[64:65], v[60:61], s[62:63] op_sel_hi:[1,1,0]
	v_exp_f32_e32 v62, v62
	v_exp_f32_e32 v63, v63
	v_pk_fma_f32 v[60:61], v[64:65], v[60:61], s[0:1] op_sel_hi:[1,1,0]
	v_cmp_gt_f32_e32 vcc, 0, v54
	v_pk_fma_f32 v[60:61], v[64:65], v[60:61], s[90:91] op_sel_hi:[1,1,0]
	v_mul_f32_e32 v51, v51, v56
	v_pk_mul_f32 v[60:61], v[64:65], v[60:61]
	s_nop 0
	v_pk_mul_f32 v[60:61], v[62:63], v[60:61]
	s_nop 0
	v_pk_mul_f32 v[62:63], v[54:55], v[60:61]
	v_pk_fma_f32 v[60:61], v[54:55], v[60:61], v[54:55] neg_lo:[1,0,0] neg_hi:[1,0,0]
	s_nop 0
	v_cndmask_b32_e32 v54, v60, v62, vcc
	v_cmp_gt_f32_e32 vcc, 0, v55
	v_cvt_pk_bf16_f32 v62, v47, v51
	v_add_f32_e32 v47, v83, v58
	v_add_f32_e32 v51, v83, v59
	v_cndmask_b32_e32 v55, v61, v63, vcc
	v_mul_f32_e32 v47, v54, v47
	v_mul_f32_e32 v51, v55, v51
	v_cvt_pk_bf16_f32 v63, v47, v51
	ds_read_b128 v[54:57], v92 offset:30464
	ds_read_b128 v[58:61], v92 offset:30528
	s_waitcnt lgkmcnt(1)
	v_mfma_f32_16x16x32_bf16 v[24:27], v[24:27], v[54:57], 0
	ds_read_b128 v[54:57], v92 offset:30592
	v_mov_b32_e32 v51, v153
	v_lshlrev_b64 v[50:51], 11, v[50:51]
	s_waitcnt lgkmcnt(1)
	v_mfma_f32_16x16x32_bf16 v[24:27], v[28:31], v[58:61], v[24:27]
	v_lshl_add_u64 v[28:29], s[86:87], 0, v[50:51]
	v_lshl_add_u64 v[50:51], v[28:29], 0, v[44:45]
	ds_read_b128 v[28:31], v92 offset:30656
	s_waitcnt lgkmcnt(1)
	v_mfma_f32_16x16x32_bf16 v[24:27], v[32:35], v[54:57], v[24:27]
	s_waitcnt vmcnt(6)
	v_lshlrev_b32_e32 v32, 16, v48
	v_and_b32_e32 v33, 0xffff0000, v48
	v_and_b32_e32 v35, 0x7fffffff, v33
	v_and_b32_e32 v34, 0x7fffffff, v32
	v_pk_fma_f32 v[34:35], v[34:35], s[78:79], 1.0 op_sel_hi:[1,0,0]
	s_waitcnt lgkmcnt(0)
	v_mfma_f32_16x16x32_bf16 v[24:27], v[36:39], v[28:31], v[24:27]
	v_rcp_f32_e32 v34, v34
	v_rcp_f32_e32 v35, v35
	v_pk_mul_f32 v[30:31], v[32:33], v[32:33]
	v_add_co_u32_e32 v50, vcc, s33, v50
	v_pk_fma_f32 v[28:29], v[34:35], s[74:75], v[52:53] op_sel_hi:[1,0,0]
	v_pk_mul_f32 v[30:31], v[30:31], s[68:69] op_sel_hi:[1,0]
	v_pk_fma_f32 v[28:29], v[34:35], v[28:29], s[62:63] op_sel_hi:[1,1,0]
	v_exp_f32_e32 v30, v30
	v_pk_fma_f32 v[28:29], v[34:35], v[28:29], s[0:1] op_sel_hi:[1,1,0]
	v_exp_f32_e32 v31, v31
	v_pk_fma_f32 v[28:29], v[34:35], v[28:29], s[90:91] op_sel_hi:[1,1,0]
	v_addc_co_u32_e32 v51, vcc, 0, v51, vcc
	v_pk_mul_f32 v[28:29], v[34:35], v[28:29]
	v_lshlrev_b32_e32 v34, 16, v49
	v_and_b32_e32 v35, 0xffff0000, v49
	v_and_b32_e32 v37, 0x7fffffff, v35
	v_and_b32_e32 v36, 0x7fffffff, v34
	v_pk_fma_f32 v[36:37], v[36:37], s[78:79], 1.0 op_sel_hi:[1,0,0]
	v_pk_mul_f32 v[28:29], v[30:31], v[28:29]
	v_rcp_f32_e32 v36, v36
	v_rcp_f32_e32 v37, v37
	v_pk_mul_f32 v[30:31], v[32:33], v[28:29]
	v_pk_fma_f32 v[28:29], v[32:33], v[28:29], v[32:33] neg_lo:[1,0,0] neg_hi:[1,0,0]
	v_cmp_gt_f32_e32 vcc, 0, v32
	v_add_f32_e32 v24, v84, v24
	v_add_f32_e32 v25, v84, v25
	v_cndmask_b32_e32 v32, v28, v30, vcc
	v_cmp_gt_f32_e32 vcc, 0, v33
	v_mul_f32_e32 v24, v32, v24
	global_store_dwordx2 v[50:51], v[62:63], off offset:1024 nt
	v_cndmask_b32_e32 v33, v29, v31, vcc
	v_pk_mul_f32 v[30:31], v[34:35], v[34:35]
	v_pk_fma_f32 v[28:29], v[36:37], s[74:75], v[52:53] op_sel_hi:[1,0,0]
	v_pk_mul_f32 v[30:31], v[30:31], s[68:69] op_sel_hi:[1,0]
	v_pk_fma_f32 v[28:29], v[36:37], v[28:29], s[62:63] op_sel_hi:[1,1,0]
	v_exp_f32_e32 v30, v30
	v_exp_f32_e32 v31, v31
	v_pk_fma_f32 v[28:29], v[36:37], v[28:29], s[0:1] op_sel_hi:[1,1,0]
	v_cmp_gt_f32_e32 vcc, 0, v34
	v_pk_fma_f32 v[28:29], v[36:37], v[28:29], s[90:91] op_sel_hi:[1,1,0]
	v_mul_f32_e32 v25, v33, v25
	v_pk_mul_f32 v[28:29], v[36:37], v[28:29]
	v_cvt_pk_bf16_f32 v24, v24, v25
	v_add_f32_e32 v25, v84, v26
	v_pk_mul_f32 v[28:29], v[30:31], v[28:29]
	v_add_f32_e32 v26, v84, v27
	v_pk_mul_f32 v[30:31], v[34:35], v[28:29]
	v_pk_fma_f32 v[28:29], v[34:35], v[28:29], v[34:35] neg_lo:[1,0,0] neg_hi:[1,0,0]
	v_mov_b32_e32 v47, v153
	v_cndmask_b32_e32 v28, v28, v30, vcc
	v_cmp_gt_f32_e32 vcc, 0, v35
	v_mul_f32_e32 v25, v28, v25
	s_nop 0
	v_cndmask_b32_e32 v29, v29, v31, vcc
	v_mul_f32_e32 v26, v29, v26
	v_cvt_pk_bf16_f32 v25, v25, v26
	v_lshlrev_b64 v[26:27], 11, v[46:47]
	v_lshl_add_u64 v[26:27], s[86:87], 0, v[26:27]
	v_lshl_add_u64 v[26:27], v[26:27], 0, v[44:45]
	v_add_co_u32_e32 v26, vcc, 0x24c00000, v26
	s_nop 1
	v_addc_co_u32_e32 v27, vcc, 0, v27, vcc
	global_store_dwordx2 v[26:27], v[24:25], off offset:1024 nt
	s_cbranch_scc0 .LBB0_251
